# final_norm: ln_final hoisted out of the row loop, next row prefetched before the current row's stores (counted vmcnt), on top of v10
# baseline (speedup 1.0000x reference)
; DI void final_norm(const Prm& p, int gw, int NGW, int lane) {
;     for (int r = gw; r < 32768 + 512; r += NGW) {
;         int grow; float* dst;
;         if (r < 32768) { const int b = r >> 12, t = r & 4095; grow = b * TP + 16 + t; dst = p.out + O_YP + (size_t)r * 1024; } else { grow = NTP + (r - 32768); dst = p.out + O_YS + (size_t)(r - 32768) * 1024; }
;         u32x2 x[4];
; #pragma unroll
;         for (int j = 0; j < 4; ++j) x[j] = ((const u32x2*)(p.XB + (size_t)grow * 1024))[lane + 64 * j];
.LBB0_2747:
	s_or_b64 exec, exec, s[0:1]
	s_cmp_gt_i32 s34, 0x81ff
	s_waitcnt lgkmcnt(0)
	s_barrier
	s_cbranch_scc1 .LBB0_2754
	v_readlane_b32 s0, v254, 12
	v_readlane_b32 s8, v254, 20
	v_readlane_b32 s1, v254, 13
	v_readlane_b32 s4, v254, 16
	v_readlane_b32 s5, v254, 17
	v_readlane_b32 s6, v254, 18
	v_readlane_b32 s7, v254, 19
	v_readlane_b32 s9, v254, 21
	v_readlane_b32 s10, v254, 22
	v_readlane_b32 s11, v254, 23
	v_readlane_b32 s12, v254, 24
	v_readlane_b32 s13, v254, 25
	v_readlane_b32 s14, v254, 26
	v_readlane_b32 s15, v254, 27
	s_add_u32 s0, s8, 0x8000000
	v_mov_b32_e32 v1, 0
	s_addc_u32 s1, s9, 0
	v_readlane_b32 s4, v254, 28
	v_lshlrev_b32_e32 v0, 4, v152
	v_readlane_b32 s3, v254, 15
	v_mov_b32_e32 v157, v1
	v_readlane_b32 s12, v254, 36
	v_readlane_b32 s13, v254, 37
	v_readlane_b32 s16, v254, 40
	v_readlane_b32 s17, v254, 41
	v_lshl_add_u64 v[2:3], s[40:41], 0, v[0:1]
	s_ashr_i32 s35, s34, 31
	v_lshl_add_u64 v[4:5], s[16:17], 0, v[156:157]
	s_ashr_i32 s12, s36, 31
	s_mov_b32 s3, 0
	v_mov_b32_e32 v0, 0x358637bd
	s_mov_b32 s13, 0x800000
	v_lshlrev_b32_e32 v6, 4, v152
	v_readlane_b32 s2, v254, 14
	v_readlane_b32 s5, v254, 29
	v_readlane_b32 s6, v254, 30
	v_readlane_b32 s7, v254, 31
	v_readlane_b32 s8, v254, 32
	v_readlane_b32 s9, v254, 33
	v_readlane_b32 s10, v254, 34
	v_readlane_b32 s11, v254, 35
	v_readlane_b32 s14, v254, 38
	v_readlane_b32 s15, v254, 39
	v_readlane_b32 s18, v254, 42
	v_readlane_b32 s19, v254, 43
	v_readlane_b32 s20, v254, 20
	v_readlane_b32 s21, v254, 21
	v_readlane_b32 s22, v254, 42
	v_readlane_b32 s23, v254, 43
	global_load_dwordx4 v[40:43], v[2:3], off
	global_load_dwordx4 v[44:47], v[2:3], off offset:1024
	global_load_dwordx4 v[48:51], v[2:3], off offset:2048
	global_load_dwordx4 v[52:55], v[2:3], off offset:3072
	s_nop 4
	s_cmpk_gt_i32 s34, 0x7fff
	s_cselect_b32 s24, s0, s20
	s_cselect_b32 s25, s1, s21
	s_cselect_b32 s14, 0x8000, 0
	s_cselect_b32 s15, 1, 0
	s_sub_i32 s16, s34, s14
	s_mov_b32 s17, 0
	s_ashr_i32 s18, s34, 12
	s_mulk_i32 s18, 0x1010
	s_and_b32 s19, s34, 0xfff
	s_add_i32 s18, s18, s19
	s_add_i32 s18, s18, 16
	s_add_i32 s19, s34, 0x80
	s_cmp_lg_u32 s15, 0
	s_cselect_b32 s26, s19, s18
	s_lshl_b64 s[16:17], s[16:17], 12
	s_add_u32 s24, s24, s16
	s_addc_u32 s25, s25, s17
	s_mov_b32 s16, s26
	s_mov_b32 s17, 0
	s_lshl_b64 s[18:19], s[16:17], 11
	s_lshl_b64 s[16:17], s[16:17], 6
	s_add_u32 s6, s22, s16
	s_addc_u32 s7, s23, s17
	v_lshl_add_u64 v[56:57], v[4:5], 0, s[18:19]
	global_load_dwordx2 v[30:31], v[56:57], off
	global_load_dwordx2 v[32:33], v[56:57], off offset:512
	global_load_dwordx2 v[34:35], v[56:57], off offset:1024
	global_load_dwordx2 v[36:37], v[56:57], off offset:1536
	global_load_dwordx4 v[8:11], v1, s[6:7]
	global_load_dwordx4 v[12:15], v1, s[6:7] offset:16
	global_load_dwordx4 v[16:19], v1, s[6:7] offset:32
	global_load_dwordx4 v[20:23], v1, s[6:7] offset:48
.Lfn_loop:
	s_add_i32 s37, s34, s36
	s_cmp_lt_i32 s37, 0x8200
	s_cbranch_scc0 .Lfn_nonext
	s_cmpk_gt_i32 s37, 0x7fff
	s_cselect_b32 s28, s0, s20
	s_cselect_b32 s29, s1, s21
	s_cselect_b32 s14, 0x8000, 0
	s_cselect_b32 s15, 1, 0
	s_sub_i32 s16, s37, s14
	s_mov_b32 s17, 0
	s_ashr_i32 s18, s37, 12
	s_mulk_i32 s18, 0x1010
	s_and_b32 s19, s37, 0xfff
	s_add_i32 s18, s18, s19
	s_add_i32 s18, s18, 16
	s_add_i32 s19, s37, 0x80
	s_cmp_lg_u32 s15, 0
	s_cselect_b32 s27, s19, s18
	s_lshl_b64 s[16:17], s[16:17], 12
	s_add_u32 s28, s28, s16
	s_addc_u32 s29, s29, s17
	s_mov_b32 s16, s27
	s_mov_b32 s17, 0
	s_lshl_b64 s[18:19], s[16:17], 11
	s_lshl_b64 s[16:17], s[16:17], 6
	s_add_u32 s6, s22, s16
	s_addc_u32 s7, s23, s17
	v_lshl_add_u64 v[56:57], v[4:5], 0, s[18:19]
	global_load_dwordx2 v[60:61], v[56:57], off
	global_load_dwordx2 v[62:63], v[56:57], off offset:512
	global_load_dwordx2 v[64:65], v[56:57], off offset:1024
	global_load_dwordx2 v[66:67], v[56:57], off offset:1536
	global_load_dwordx4 v[68:71], v1, s[6:7]
	global_load_dwordx4 v[72:75], v1, s[6:7] offset:16
	global_load_dwordx4 v[76:79], v1, s[6:7] offset:32
	global_load_dwordx4 v[80:83], v1, s[6:7] offset:48
	s_waitcnt vmcnt(8)
	s_branch .Lfn_compute

; DI float bflo(unsigned u) { return __uint_as_float(u << 16); }
; DI float bfhi(unsigned u) { return __uint_as_float(u & 0xffff0000u); }
; DI float row_rinv(const float* SSQ, int row) {
;     const f32x4* s = (const f32x4*)(SSQ + (size_t)row * 16); f32x4 a = s[0] + s[1] + s[2] + s[3];
;     return rsqrtf(((a.x + a.y) + (a.z + a.w)) * (1.f / 1024.f) + EPSN);
; }
; DI void final_norm(const Prm& p, int gw, int NGW, int lane) {
;     ...
;         const float rr = row_rinv(p.SSQ, grow);
; #pragma unroll
;         for (int j = 0; j < 4; ++j) { f32x4 v; v.x = bflo(x[j].x); v.y = bfhi(x[j].x); v.z = bflo(x[j].y); v.w = bfhi(x[j].y); ((f32x4*)dst)[lane + 64 * j] = v * rr * ((const f32x4*)p.ln_final)[lane + 64 * j]; }
;     }
.Lfn_compute:
	v_pk_add_f32 v[10:11], v[10:11], v[14:15]
	v_pk_add_f32 v[8:9], v[8:9], v[12:13]
	v_pk_add_f32 v[10:11], v[10:11], v[18:19]
	v_pk_add_f32 v[8:9], v[8:9], v[16:17]
	v_pk_add_f32 v[10:11], v[10:11], v[22:23]
	v_pk_add_f32 v[8:9], v[8:9], v[20:21]
	s_nop 0
	v_mov_b32_e32 v13, v10
	v_mov_b32_e32 v12, v9
	v_mov_b32_e32 v9, v11
	s_nop 0
	v_pk_add_f32 v[8:9], v[12:13], v[8:9]
	s_nop 0
	v_add_f32_e32 v7, v8, v9
	v_fmamk_f32 v7, v7, 0x3a800000, v0
	v_cmp_gt_f32_e32 vcc, s13, v7
	v_mul_f32_e32 v8, 0x4b800000, v7
	s_nop 1
	v_cndmask_b32_e32 v7, v7, v8, vcc
	v_rsq_f32_e32 v7, v7
	s_nop 0
	v_mul_f32_e32 v10, 0x45800000, v7
	v_cndmask_b32_e32 v12, v7, v10, vcc
	v_lshlrev_b32_e32 v100, 16, v30
	v_and_b32_e32 v101, 0xffff0000, v30
	v_lshlrev_b32_e32 v102, 16, v31
	v_and_b32_e32 v103, 0xffff0000, v31
	v_pk_mul_f32 v[100:101], v[12:13], v[100:101] op_sel_hi:[0,1]
	v_pk_mul_f32 v[102:103], v[12:13], v[102:103] op_sel_hi:[0,1]
	v_pk_mul_f32 v[84:85], v[40:41], v[100:101]
	v_pk_mul_f32 v[86:87], v[42:43], v[102:103]
	global_store_dwordx4 v6, v[84:87], s[24:25] offset:0
	v_lshlrev_b32_e32 v100, 16, v32
	v_and_b32_e32 v101, 0xffff0000, v32
	v_lshlrev_b32_e32 v102, 16, v33
	v_and_b32_e32 v103, 0xffff0000, v33
	v_pk_mul_f32 v[100:101], v[12:13], v[100:101] op_sel_hi:[0,1]
	v_pk_mul_f32 v[102:103], v[12:13], v[102:103] op_sel_hi:[0,1]
	v_pk_mul_f32 v[88:89], v[44:45], v[100:101]
	v_pk_mul_f32 v[90:91], v[46:47], v[102:103]
	global_store_dwordx4 v6, v[88:91], s[24:25] offset:1024
	v_lshlrev_b32_e32 v100, 16, v34
	v_and_b32_e32 v101, 0xffff0000, v34
	v_lshlrev_b32_e32 v102, 16, v35
	v_and_b32_e32 v103, 0xffff0000, v35
	v_pk_mul_f32 v[100:101], v[12:13], v[100:101] op_sel_hi:[0,1]
	v_pk_mul_f32 v[102:103], v[12:13], v[102:103] op_sel_hi:[0,1]
	v_pk_mul_f32 v[92:93], v[48:49], v[100:101]
	v_pk_mul_f32 v[94:95], v[50:51], v[102:103]
	global_store_dwordx4 v6, v[92:95], s[24:25] offset:2048
	v_lshlrev_b32_e32 v100, 16, v36
	v_and_b32_e32 v101, 0xffff0000, v36
	v_lshlrev_b32_e32 v102, 16, v37
	v_and_b32_e32 v103, 0xffff0000, v37
	v_pk_mul_f32 v[100:101], v[12:13], v[100:101] op_sel_hi:[0,1]
	v_pk_mul_f32 v[102:103], v[12:13], v[102:103] op_sel_hi:[0,1]
	v_pk_mul_f32 v[96:97], v[52:53], v[100:101]
	v_pk_mul_f32 v[98:99], v[54:55], v[102:103]
	global_store_dwordx4 v6, v[96:99], s[24:25] offset:3072
	s_cmp_lt_i32 s37, 0x8200
	s_cbranch_scc0 .LBB0_2754
	s_mov_b32 s34, s37
	s_mov_b64 s[24:25], s[28:29]
	s_waitcnt vmcnt(4)
	v_mov_b64_e32 v[30:31], v[60:61]
	v_mov_b64_e32 v[32:33], v[62:63]
	v_mov_b64_e32 v[34:35], v[64:65]
	v_mov_b64_e32 v[36:37], v[66:67]
	v_mov_b64_e32 v[8:9], v[68:69]
	v_mov_b64_e32 v[10:11], v[70:71]
	v_mov_b64_e32 v[12:13], v[72:73]
	v_mov_b64_e32 v[14:15], v[74:75]
	v_mov_b64_e32 v[16:17], v[76:77]
	v_mov_b64_e32 v[18:19], v[78:79]
	v_mov_b64_e32 v[20:21], v[80:81]
	v_mov_b64_e32 v[22:23], v[82:83]
	s_branch .Lfn_loop
